# FFN-up K-loop LDS-DMAs in SGPR-base form (no 64-bit VALU address adds), on the no-setprio stack
# speedup vs baseline: 1.0008x; 1.0008x over previous
; #define PG8_STAGE(bufoff, gbase, voff) do { _Pragma("unroll") for (int _i = 0; _i < 2; ++_i) \
;         __builtin_amdgcn_global_load_lds((const unsigned*)((const char*)(gbase) + (voff)[_i]), (PG8_LAS unsigned*)(lds + (bufoff) + ldsw + _i * 8192), 16, 0, 0); } while (0)
; #define PG8_LDA(dst, b, h) do { _Pragma("unroll") for (int m = 0; m < 4; ++m) _Pragma("unroll") for (int k = 0; k < 2; ++k) dst[m][k] = *(const PG8_LAS bf16x8*)(lds + PG8_SA(b, h) + aoff + m * 2048 + k * 1024); } while (0)
; #define PG8_LDB(dst, b, h) do { _Pragma("unroll") for (int n = 0; n < 2; ++n) _Pragma("unroll") for (int k = 0; k < 2; ++k) dst[n][k] = *(const PG8_LAS bf16x8*)(lds + PG8_SB(b, h) + boff + n * 2048 + k * 1024); } while (0)
; #define PG8_WAIT_V(n) asm volatile("s_waitcnt vmcnt(" #n ")" ::: "memory")
; #define PG8_WAIT_L(n) asm volatile("s_waitcnt lgkmcnt(" #n ")" ::: "memory")
; #define PG8_BAR __builtin_amdgcn_s_barrier()
; #define PG8_SCHED __builtin_amdgcn_sched_barrier(0)
; template <class Epi, class Sched, bool ALIGN_EPI = false, bool SP2 = false>
; __device__ __forceinline__ void gemm_phase(PG8_LAS unsigned char* lds, const Gemm g, const Sched& S, const Epi& E, const int tid_) {
;     ...
;         const bool has_next = S.next(ui + 1, nxt);
;         const char* nA = has_next ? (const char*)g.A + (size_t)nxt.pm * tstep : cA; const char* nB = has_next ? (const char*)g.Bt + (size_t)nxt.pn * tstep : cB;
;         for (int t = 0; t < nt; t += 2) {
;             const bool last = (t == nt - 2);
;             const char* a1 = cA + (size_t)(t + 1) * kstep;
;             const char* a2 = last ? nA : cA + (size_t)(t + 2) * kstep; const char* b2 = last ? nB : cB + (size_t)(t + 2) * kstep;
;             const char* a3 = a2 + kstep; const char* b3 = b2 + kstep;
;             if (last && has_next) S.a_ready(nxt);
;             if constexpr (SP2) {
;             PG8_LDB(B0, 0, 0); PG8_LDB(B1, 0, 1); PG8_SCHED; PG8_LDA(At, 0, 0); PG8_STAGE(PG8_SA(1, 1), a1 + hstep, voffA);
;             PG8_WAIT_V(8); PG8_WAIT_L(0); PG8_BAR; PG8_MMA(0, 0, At, B0); PG8_MMA(0, 1, At, B1); PG8_BAR; PG8_SCHED;
;             PG8_LDA(At, 0, 1); PG8_STAGE(PG8_SB(0, 0), b2, voffB); PG8_STAGE(PG8_SB(0, 1), b2 + hstepB, voffB); PG8_STAGE(PG8_SA(0, 0), a2, voffA);
;             PG8_WAIT_V(8); PG8_WAIT_L(0); PG8_BAR; PG8_MMA(1, 0, At, B0); PG8_MMA(1, 1, At, B1); PG8_BAR; PG8_SCHED;
.LBB0_23:
	s_ashr_i32 s17, s16, 31
	s_lshl_b64 s[2:3], s[16:17], 19
	s_add_u32 s18, s78, s2
	s_addc_u32 s19, s79, s3
	s_and_b64 s[2:3], s[6:7], exec
	s_cselect_b32 s2, s19, s25
	s_cselect_b32 s3, s18, s24
	s_ashr_i32 s15, s14, 31
	s_lshl_b64 s[20:21], s[14:15], 19
	s_add_u32 s20, s30, s20
	s_addc_u32 s21, s31, s21
	s_and_b64 s[28:29], s[6:7], exec
	s_cselect_b32 s15, s21, s27
	s_cselect_b32 s17, s20, s26
	s_add_u32 s24, s24, 0x40080
	s_addc_u32 s25, s25, 0
	s_add_u32 s55, s26, 0x100
	s_addc_u32 s56, s27, 0
	s_mov_b32 s57, -2
	v_add_u32_e32 v154, s23, v163
	v_add_u32_e32 v174, s37, v163
	ds_read_b128 v[132:135], v154
	ds_read_b128 v[146:149], v154 offset:1024
	ds_read_b128 v[150:153], v154 offset:2048
	ds_read_b128 v[154:157], v154 offset:3072
	ds_read_b128 v[158:161], v174
	ds_read_b128 v[166:169], v174 offset:1024
	ds_read_b128 v[170:173], v174 offset:2048
	ds_read_b128 v[174:177], v174 offset:3072
	s_add_u32 s26, s24, 0xfffc0080
	s_addc_u32 s27, s25, -1
	s_cmp_eq_u32 s57, 12
	s_cselect_b32 s29, s2, s27
	s_cselect_b32 s28, s3, s26
	s_cselect_b32 s27, s15, s56
	s_cselect_b32 s26, s17, s55
	s_add_i32 m0, s40, 0xc000
	ds_read_b128 v[188:191], v165
	ds_read_b128 v[192:195], v165 offset:1024
	ds_read_b128 v[196:199], v165 offset:2048
	ds_read_b128 v[200:203], v165 offset:3072
	ds_read_b128 v[204:207], v165 offset:4096
	ds_read_b128 v[208:211], v165 offset:5120
	ds_read_b128 v[212:215], v165 offset:6144
	ds_read_b128 v[216:219], v165 offset:7168
	global_load_lds_dwordx4 v142, s[24:25]
	s_add_i32 m0, s40, 0xe000
	s_nop 0
	global_load_lds_dwordx4 v144, s[24:25]
	s_cmp_lg_u32 s53, 1
	s_cbranch_scc1 .Lpeel1_w1
	s_waitcnt vmcnt(8)
.Lpeel1_w1:
	s_waitcnt lgkmcnt(0)
	s_barrier
	s_waitcnt lgkmcnt(0)
	v_mfma_f32_16x16x32_bf16 v[128:131], v[132:135], v[188:191], 0
	v_mfma_f32_16x16x32_bf16 v[120:123], v[150:153], v[188:191], 0
	v_mfma_f32_16x16x32_bf16 v[112:115], v[132:135], v[196:199], 0
	v_mfma_f32_16x16x32_bf16 v[104:107], v[150:153], v[196:199], 0
	v_mfma_f32_16x16x32_bf16 v[96:99], v[132:135], v[204:207], 0
	v_mfma_f32_16x16x32_bf16 v[88:91], v[150:153], v[204:207], 0
	v_mfma_f32_16x16x32_bf16 v[80:83], v[132:135], v[212:215], 0
	v_mfma_f32_16x16x32_bf16 v[72:75], v[150:153], v[212:215], 0
	v_mfma_f32_16x16x32_bf16 v[128:131], v[146:149], v[192:195], v[128:131]
	v_mfma_f32_16x16x32_bf16 v[120:123], v[154:157], v[192:195], v[120:123]
	v_mfma_f32_16x16x32_bf16 v[112:115], v[146:149], v[200:203], v[112:115]
	v_mfma_f32_16x16x32_bf16 v[104:107], v[154:157], v[200:203], v[104:107]
	v_mfma_f32_16x16x32_bf16 v[96:99], v[146:149], v[208:211], v[96:99]
	v_mfma_f32_16x16x32_bf16 v[88:91], v[154:157], v[208:211], v[88:91]
	v_mfma_f32_16x16x32_bf16 v[80:83], v[146:149], v[216:219], v[80:83]
	v_mfma_f32_16x16x32_bf16 v[72:75], v[154:157], v[216:219], v[72:75]
	v_mfma_f32_16x16x32_bf16 v[124:127], v[158:161], v[188:191], 0
	v_mfma_f32_16x16x32_bf16 v[116:119], v[170:173], v[188:191], 0
	v_mfma_f32_16x16x32_bf16 v[108:111], v[158:161], v[196:199], 0
	v_mfma_f32_16x16x32_bf16 v[100:103], v[170:173], v[196:199], 0
	v_mfma_f32_16x16x32_bf16 v[92:95], v[158:161], v[204:207], 0
	v_mfma_f32_16x16x32_bf16 v[84:87], v[170:173], v[204:207], 0
	v_mfma_f32_16x16x32_bf16 v[76:79], v[158:161], v[212:215], 0
	v_mfma_f32_16x16x32_bf16 v[68:71], v[170:173], v[212:215], 0
	v_mfma_f32_16x16x32_bf16 v[124:127], v[166:169], v[192:195], v[124:127]
	v_mfma_f32_16x16x32_bf16 v[116:119], v[174:177], v[192:195], v[116:119]
	v_mfma_f32_16x16x32_bf16 v[108:111], v[166:169], v[200:203], v[108:111]
	v_mfma_f32_16x16x32_bf16 v[100:103], v[174:177], v[200:203], v[100:103]
	v_mfma_f32_16x16x32_bf16 v[92:95], v[166:169], v[208:211], v[92:95]
	v_mfma_f32_16x16x32_bf16 v[84:87], v[174:177], v[208:211], v[84:87]
	v_mfma_f32_16x16x32_bf16 v[76:79], v[166:169], v[216:219], v[76:79]
	v_mfma_f32_16x16x32_bf16 v[68:71], v[174:177], v[216:219], v[68:71]
	s_barrier
	s_mov_b32 m0, s35
	s_add_u32 s58, s26, 0x40000
	ds_read_b128 v[188:191], v165 offset:16384
	ds_read_b128 v[192:195], v165 offset:17408
	ds_read_b128 v[196:199], v165 offset:18432
	ds_read_b128 v[200:203], v165 offset:19456
	ds_read_b128 v[204:207], v165 offset:20480
	ds_read_b128 v[208:211], v165 offset:21504
	ds_read_b128 v[212:215], v165 offset:22528
	ds_read_b128 v[216:219], v165 offset:23552
	global_load_lds_dwordx4 v2, s[26:27]
	s_mov_b32 m0, s36
	s_addc_u32 s59, s27, 0
	global_load_lds_dwordx4 v0, s[26:27]
	s_mov_b32 m0, s38
	s_nop 0
	global_load_lds_dwordx4 v2, s[58:59]
	s_mov_b32 m0, s39
	s_nop 0
	global_load_lds_dwordx4 v0, s[58:59]
	s_mov_b32 m0, s40
	s_nop 0
	global_load_lds_dwordx4 v138, s[28:29]
	s_mov_b32 m0, s41
	s_nop 0
	global_load_lds_dwordx4 v136, s[28:29]
	s_cmp_lg_u32 s53, 1
	s_cbranch_scc1 .Lpeel1_w2
	s_waitcnt vmcnt(8)
; #define PG8_STAGE(bufoff, gbase, voff) do { _Pragma("unroll") for (int _i = 0; _i < 2; ++_i) \
;         __builtin_amdgcn_global_load_lds((const unsigned*)((const char*)(gbase) + (voff)[_i]), (PG8_LAS unsigned*)(lds + (bufoff) + ldsw + _i * 8192), 16, 0, 0); } while (0)
; #define PG8_LDA(dst, b, h) do { _Pragma("unroll") for (int m = 0; m < 4; ++m) _Pragma("unroll") for (int k = 0; k < 2; ++k) dst[m][k] = *(const PG8_LAS bf16x8*)(lds + PG8_SA(b, h) + aoff + m * 2048 + k * 1024); } while (0)
; #define PG8_LDB(dst, b, h) do { _Pragma("unroll") for (int n = 0; n < 2; ++n) _Pragma("unroll") for (int k = 0; k < 2; ++k) dst[n][k] = *(const PG8_LAS bf16x8*)(lds + PG8_SB(b, h) + boff + n * 2048 + k * 1024); } while (0)
; #define PG8_MMA(ai, bj, At, Bt) do { __builtin_amdgcn_s_setprio(1); _Pragma("unroll") for (int m = 0; m < 4; ++m) _Pragma("unroll") for (int n = 0; n < 2; ++n) _Pragma("unroll") for (int k = 0; k < 2; ++k) \
;         acc[ai][bj][m][n] = __builtin_amdgcn_mfma_f32_16x16x32_bf16(Bt[n][k], At[m][k], acc[ai][bj][m][n], 0, 0, 0); __builtin_amdgcn_s_setprio(0); } while (0)
; #define PG8_WAIT_V(n) asm volatile("s_waitcnt vmcnt(" #n ")" ::: "memory")
; #define PG8_WAIT_L(n) asm volatile("s_waitcnt lgkmcnt(" #n ")" ::: "memory")
; #define PG8_BAR __builtin_amdgcn_s_barrier()
; #define PG8_SCHED __builtin_amdgcn_sched_barrier(0)
; template <class Epi, class Sched, bool ALIGN_EPI = false, bool SP2 = false>
; __device__ __forceinline__ void gemm_phase(PG8_LAS unsigned char* lds, const Gemm g, const Sched& S, const Epi& E, const int tid_) {
;     ...
;             PG8_WAIT_V(8); PG8_WAIT_L(0); PG8_BAR; PG8_MMA(1, 0, At, B0); PG8_MMA(1, 1, At, B1); PG8_BAR; PG8_SCHED;
;             PG8_LDB(B0, 1, 0); PG8_LDB(B1, 1, 1); PG8_SCHED; PG8_LDA(At, 1, 0); PG8_STAGE(PG8_SA(0, 1), a2 + hstep, voffA);
;             PG8_WAIT_V(8); PG8_WAIT_L(0); PG8_BAR; PG8_MMA(0, 0, At, B0); PG8_MMA(0, 1, At, B1); PG8_BAR; PG8_SCHED;
.Lpeel1_w2:
	s_waitcnt lgkmcnt(0)
	s_barrier
	s_waitcnt lgkmcnt(0)
	v_mfma_f32_16x16x32_bf16 v[64:67], v[132:135], v[188:191], 0
	v_mfma_f32_16x16x32_bf16 v[56:59], v[150:153], v[188:191], 0
	v_mfma_f32_16x16x32_bf16 v[48:51], v[132:135], v[196:199], 0
	v_mfma_f32_16x16x32_bf16 v[40:43], v[150:153], v[196:199], 0
	v_mfma_f32_16x16x32_bf16 v[32:35], v[132:135], v[204:207], 0
	v_mfma_f32_16x16x32_bf16 v[24:27], v[150:153], v[204:207], 0
	v_mfma_f32_16x16x32_bf16 v[16:19], v[132:135], v[212:215], 0
	v_mfma_f32_16x16x32_bf16 v[8:11], v[150:153], v[212:215], 0
	v_mfma_f32_16x16x32_bf16 v[64:67], v[146:149], v[192:195], v[64:67]
	v_mfma_f32_16x16x32_bf16 v[56:59], v[154:157], v[192:195], v[56:59]
	v_mfma_f32_16x16x32_bf16 v[48:51], v[146:149], v[200:203], v[48:51]
	v_mfma_f32_16x16x32_bf16 v[40:43], v[154:157], v[200:203], v[40:43]
	v_mfma_f32_16x16x32_bf16 v[32:35], v[146:149], v[208:211], v[32:35]
	v_mfma_f32_16x16x32_bf16 v[24:27], v[154:157], v[208:211], v[24:27]
	v_mfma_f32_16x16x32_bf16 v[16:19], v[146:149], v[216:219], v[16:19]
	v_mfma_f32_16x16x32_bf16 v[8:11], v[154:157], v[216:219], v[8:11]
	v_mfma_f32_16x16x32_bf16 v[60:63], v[158:161], v[188:191], 0
	v_mfma_f32_16x16x32_bf16 v[52:55], v[170:173], v[188:191], 0
	v_mfma_f32_16x16x32_bf16 v[44:47], v[158:161], v[196:199], 0
	v_mfma_f32_16x16x32_bf16 v[36:39], v[170:173], v[196:199], 0
	v_mfma_f32_16x16x32_bf16 v[28:31], v[158:161], v[204:207], 0
	v_mfma_f32_16x16x32_bf16 v[20:23], v[170:173], v[204:207], 0
	v_mfma_f32_16x16x32_bf16 v[12:15], v[158:161], v[212:215], 0
	v_mfma_f32_16x16x32_bf16 v[4:7], v[170:173], v[212:215], 0
	v_mfma_f32_16x16x32_bf16 v[60:63], v[166:169], v[192:195], v[60:63]
	v_mfma_f32_16x16x32_bf16 v[52:55], v[174:177], v[192:195], v[52:55]
	v_mfma_f32_16x16x32_bf16 v[44:47], v[166:169], v[200:203], v[44:47]
	v_mfma_f32_16x16x32_bf16 v[36:39], v[174:177], v[200:203], v[36:39]
	v_mfma_f32_16x16x32_bf16 v[28:31], v[166:169], v[208:211], v[28:31]
	v_mfma_f32_16x16x32_bf16 v[20:23], v[174:177], v[208:211], v[20:23]
	v_mfma_f32_16x16x32_bf16 v[12:15], v[166:169], v[216:219], v[12:15]
	v_mfma_f32_16x16x32_bf16 v[4:7], v[174:177], v[216:219], v[4:7]
	s_barrier
	v_add_u32_e32 v154, s44, v163
	v_add_u32_e32 v174, s49, v163
	ds_read_b128 v[132:135], v154
	ds_read_b128 v[146:149], v154 offset:1024
	ds_read_b128 v[150:153], v154 offset:2048
	ds_read_b128 v[154:157], v154 offset:3072
	ds_read_b128 v[158:161], v174
	ds_read_b128 v[166:169], v174 offset:1024
	ds_read_b128 v[170:173], v174 offset:2048
	ds_read_b128 v[174:177], v174 offset:3072
	s_add_u32 s28, s28, 0x40000
	s_addc_u32 s29, s29, 0
	s_mov_b32 m0, s42
	ds_read_b128 v[188:191], v165 offset:32768
	ds_read_b128 v[192:195], v165 offset:33792
	ds_read_b128 v[196:199], v165 offset:34816
	ds_read_b128 v[200:203], v165 offset:35840
	ds_read_b128 v[204:207], v165 offset:36864
	ds_read_b128 v[208:211], v165 offset:37888
	ds_read_b128 v[212:215], v165 offset:38912
	ds_read_b128 v[216:219], v165 offset:39936
	global_load_lds_dwordx4 v138, s[28:29]
	s_mov_b32 m0, s43
	s_nop 0
	global_load_lds_dwordx4 v136, s[28:29]
	s_waitcnt vmcnt(8)
	s_waitcnt lgkmcnt(0)
	s_barrier
	s_waitcnt lgkmcnt(0)
	v_mfma_f32_16x16x32_bf16 v[128:131], v[132:135], v[188:191], v[128:131]
	v_mfma_f32_16x16x32_bf16 v[120:123], v[150:153], v[188:191], v[120:123]
	v_mfma_f32_16x16x32_bf16 v[112:115], v[132:135], v[196:199], v[112:115]
	v_mfma_f32_16x16x32_bf16 v[104:107], v[150:153], v[196:199], v[104:107]
	v_mfma_f32_16x16x32_bf16 v[96:99], v[132:135], v[204:207], v[96:99]
	v_mfma_f32_16x16x32_bf16 v[88:91], v[150:153], v[204:207], v[88:91]
	v_mfma_f32_16x16x32_bf16 v[80:83], v[132:135], v[212:215], v[80:83]
	v_mfma_f32_16x16x32_bf16 v[72:75], v[150:153], v[212:215], v[72:75]
	v_mfma_f32_16x16x32_bf16 v[128:131], v[146:149], v[192:195], v[128:131]
	v_mfma_f32_16x16x32_bf16 v[120:123], v[154:157], v[192:195], v[120:123]
	v_mfma_f32_16x16x32_bf16 v[112:115], v[146:149], v[200:203], v[112:115]
	v_mfma_f32_16x16x32_bf16 v[104:107], v[154:157], v[200:203], v[104:107]
	v_mfma_f32_16x16x32_bf16 v[96:99], v[146:149], v[208:211], v[96:99]
	v_mfma_f32_16x16x32_bf16 v[88:91], v[154:157], v[208:211], v[88:91]
	v_mfma_f32_16x16x32_bf16 v[80:83], v[146:149], v[216:219], v[80:83]
	v_mfma_f32_16x16x32_bf16 v[72:75], v[154:157], v[216:219], v[72:75]
	v_mfma_f32_16x16x32_bf16 v[124:127], v[158:161], v[188:191], v[124:127]
	v_mfma_f32_16x16x32_bf16 v[116:119], v[170:173], v[188:191], v[116:119]
	v_mfma_f32_16x16x32_bf16 v[108:111], v[158:161], v[196:199], v[108:111]
	v_mfma_f32_16x16x32_bf16 v[100:103], v[170:173], v[196:199], v[100:103]
	v_mfma_f32_16x16x32_bf16 v[92:95], v[158:161], v[204:207], v[92:95]
	v_mfma_f32_16x16x32_bf16 v[84:87], v[170:173], v[204:207], v[84:87]
	v_mfma_f32_16x16x32_bf16 v[76:79], v[158:161], v[212:215], v[76:79]
	v_mfma_f32_16x16x32_bf16 v[68:71], v[170:173], v[212:215], v[68:71]
	v_mfma_f32_16x16x32_bf16 v[124:127], v[166:169], v[192:195], v[124:127]
	v_mfma_f32_16x16x32_bf16 v[116:119], v[174:177], v[192:195], v[116:119]
	v_mfma_f32_16x16x32_bf16 v[108:111], v[166:169], v[200:203], v[108:111]
	v_mfma_f32_16x16x32_bf16 v[100:103], v[174:177], v[200:203], v[100:103]
	v_mfma_f32_16x16x32_bf16 v[92:95], v[166:169], v[208:211], v[92:95]
	v_mfma_f32_16x16x32_bf16 v[84:87], v[174:177], v[208:211], v[84:87]
	v_mfma_f32_16x16x32_bf16 v[76:79], v[166:169], v[216:219], v[76:79]
	v_mfma_f32_16x16x32_bf16 v[68:71], v[174:177], v[216:219], v[68:71]
	s_barrier
; #define PG8_STAGE(bufoff, gbase, voff) do { _Pragma("unroll") for (int _i = 0; _i < 2; ++_i) \
;         __builtin_amdgcn_global_load_lds((const unsigned*)((const char*)(gbase) + (voff)[_i]), (PG8_LAS unsigned*)(lds + (bufoff) + ldsw + _i * 8192), 16, 0, 0); } while (0)
; #define PG8_LDA(dst, b, h) do { _Pragma("unroll") for (int m = 0; m < 4; ++m) _Pragma("unroll") for (int k = 0; k < 2; ++k) dst[m][k] = *(const PG8_LAS bf16x8*)(lds + PG8_SA(b, h) + aoff + m * 2048 + k * 1024); } while (0)
; #define PG8_LDB(dst, b, h) do { _Pragma("unroll") for (int n = 0; n < 2; ++n) _Pragma("unroll") for (int k = 0; k < 2; ++k) dst[n][k] = *(const PG8_LAS bf16x8*)(lds + PG8_SB(b, h) + boff + n * 2048 + k * 1024); } while (0)
; #define PG8_MMA(ai, bj, At, Bt) do { __builtin_amdgcn_s_setprio(1); _Pragma("unroll") for (int m = 0; m < 4; ++m) _Pragma("unroll") for (int n = 0; n < 2; ++n) _Pragma("unroll") for (int k = 0; k < 2; ++k) \
;         acc[ai][bj][m][n] = __builtin_amdgcn_mfma_f32_16x16x32_bf16(Bt[n][k], At[m][k], acc[ai][bj][m][n], 0, 0, 0); __builtin_amdgcn_s_setprio(0); } while (0)
; #define PG8_WAIT_V(n) asm volatile("s_waitcnt vmcnt(" #n ")" ::: "memory")
; #define PG8_WAIT_L(n) asm volatile("s_waitcnt lgkmcnt(" #n ")" ::: "memory")
; #define PG8_BAR __builtin_amdgcn_s_barrier()
; #define PG8_SCHED __builtin_amdgcn_sched_barrier(0)
; template <class Epi, class Sched, bool ALIGN_EPI = false, bool SP2 = false>
; __device__ __forceinline__ void gemm_phase(PG8_LAS unsigned char* lds, const Gemm g, const Sched& S, const Epi& E, const int tid_) {
;     ...
;             PG8_LDB(B0, 0, 0); PG8_LDB(B1, 0, 1); PG8_SCHED; PG8_LDA(At, 0, 0); PG8_STAGE(PG8_SA(1, 1), a1 + hstep, voffA);
;             PG8_WAIT_V(8); PG8_WAIT_L(0); PG8_BAR; PG8_MMA(0, 0, At, B0); PG8_MMA(0, 1, At, B1); PG8_BAR; PG8_SCHED;
;     ...
;             PG8_LDA(At, 1, 1); PG8_STAGE(PG8_SB(1, 0), b3, voffB); PG8_STAGE(PG8_SB(1, 1), b3 + hstepB, voffB); PG8_STAGE(PG8_SA(1, 0), a3, voffA);
;             PG8_WAIT_V(8); PG8_WAIT_L(0); PG8_BAR; PG8_MMA(1, 0, At, B0); PG8_MMA(1, 1, At, B1); PG8_BAR; PG8_SCHED;
	s_mov_b32 m0, s45
	s_add_u32 s58, s26, 0x80
	s_addc_u32 s59, s27, 0
	s_add_u32 s26, s26, 0x40080
	s_addc_u32 s27, s27, 0
	ds_read_b128 v[188:191], v165 offset:49152
	ds_read_b128 v[192:195], v165 offset:50176
	ds_read_b128 v[196:199], v165 offset:51200
	ds_read_b128 v[200:203], v165 offset:52224
	ds_read_b128 v[204:207], v165 offset:53248
	ds_read_b128 v[208:211], v165 offset:54272
	ds_read_b128 v[212:215], v165 offset:55296
	ds_read_b128 v[216:219], v165 offset:56320
	global_load_lds_dwordx4 v2, s[58:59]
	s_mov_b32 m0, s46
	s_add_u32 s28, s28, 0xfffc0080
	s_addc_u32 s29, s29, -1
	global_load_lds_dwordx4 v0, s[58:59]
	s_mov_b32 m0, s50
	s_nop 0
	global_load_lds_dwordx4 v2, s[26:27]
	s_mov_b32 m0, s51
	s_nop 0
	global_load_lds_dwordx4 v0, s[26:27]
	s_mov_b32 m0, s47
	s_nop 0
	global_load_lds_dwordx4 v138, s[28:29]
	s_mov_b32 m0, s48
	s_nop 0
	global_load_lds_dwordx4 v136, s[28:29]
	s_waitcnt vmcnt(8)
	s_waitcnt lgkmcnt(0)
	s_barrier
	s_waitcnt lgkmcnt(0)
	v_mfma_f32_16x16x32_bf16 v[64:67], v[132:135], v[188:191], v[64:67]
	v_mfma_f32_16x16x32_bf16 v[56:59], v[150:153], v[188:191], v[56:59]
	v_mfma_f32_16x16x32_bf16 v[48:51], v[132:135], v[196:199], v[48:51]
	v_mfma_f32_16x16x32_bf16 v[40:43], v[150:153], v[196:199], v[40:43]
	v_mfma_f32_16x16x32_bf16 v[32:35], v[132:135], v[204:207], v[32:35]
	v_mfma_f32_16x16x32_bf16 v[24:27], v[150:153], v[204:207], v[24:27]
	v_mfma_f32_16x16x32_bf16 v[16:19], v[132:135], v[212:215], v[16:19]
	v_mfma_f32_16x16x32_bf16 v[8:11], v[150:153], v[212:215], v[8:11]
	v_mfma_f32_16x16x32_bf16 v[64:67], v[146:149], v[192:195], v[64:67]
	v_mfma_f32_16x16x32_bf16 v[56:59], v[154:157], v[192:195], v[56:59]
	v_mfma_f32_16x16x32_bf16 v[48:51], v[146:149], v[200:203], v[48:51]
	v_mfma_f32_16x16x32_bf16 v[40:43], v[154:157], v[200:203], v[40:43]
	v_mfma_f32_16x16x32_bf16 v[32:35], v[146:149], v[208:211], v[32:35]
	v_mfma_f32_16x16x32_bf16 v[24:27], v[154:157], v[208:211], v[24:27]
	v_mfma_f32_16x16x32_bf16 v[16:19], v[146:149], v[216:219], v[16:19]
	v_mfma_f32_16x16x32_bf16 v[8:11], v[154:157], v[216:219], v[8:11]
	v_mfma_f32_16x16x32_bf16 v[60:63], v[158:161], v[188:191], v[60:63]
	v_mfma_f32_16x16x32_bf16 v[52:55], v[170:173], v[188:191], v[52:55]
	v_mfma_f32_16x16x32_bf16 v[44:47], v[158:161], v[196:199], v[44:47]
	v_mfma_f32_16x16x32_bf16 v[36:39], v[170:173], v[196:199], v[36:39]
	v_mfma_f32_16x16x32_bf16 v[28:31], v[158:161], v[204:207], v[28:31]
	v_mfma_f32_16x16x32_bf16 v[20:23], v[170:173], v[204:207], v[20:23]
	v_mfma_f32_16x16x32_bf16 v[12:15], v[158:161], v[212:215], v[12:15]
	v_mfma_f32_16x16x32_bf16 v[4:7], v[170:173], v[212:215], v[4:7]
	v_mfma_f32_16x16x32_bf16 v[60:63], v[166:169], v[192:195], v[60:63]
	v_mfma_f32_16x16x32_bf16 v[52:55], v[174:177], v[192:195], v[52:55]
	v_mfma_f32_16x16x32_bf16 v[44:47], v[166:169], v[200:203], v[44:47]
	v_mfma_f32_16x16x32_bf16 v[36:39], v[174:177], v[200:203], v[36:39]
	v_mfma_f32_16x16x32_bf16 v[28:31], v[166:169], v[208:211], v[28:31]
	v_mfma_f32_16x16x32_bf16 v[20:23], v[174:177], v[208:211], v[20:23]
	v_mfma_f32_16x16x32_bf16 v[12:15], v[166:169], v[216:219], v[12:15]
	v_mfma_f32_16x16x32_bf16 v[4:7], v[174:177], v[216:219], v[4:7]
	s_barrier
	s_add_i32 s57, s57, 2
	s_add_u32 s24, s24, 0x100
	s_addc_u32 s25, s25, 0
	s_add_u32 s55, s55, 0x100
	s_addc_u32 s56, s56, 0
.LBB0_24:
	v_add_u32_e32 v154, s23, v163
	v_add_u32_e32 v174, s37, v163
	ds_read_b128 v[132:135], v154
	ds_read_b128 v[146:149], v154 offset:1024
	ds_read_b128 v[150:153], v154 offset:2048
	ds_read_b128 v[154:157], v154 offset:3072
	ds_read_b128 v[158:161], v174
	ds_read_b128 v[166:169], v174 offset:1024
	ds_read_b128 v[170:173], v174 offset:2048
	ds_read_b128 v[174:177], v174 offset:3072
	s_add_u32 s26, s24, 0xfffc0080
	s_addc_u32 s27, s25, -1
	s_cmp_eq_u32 s57, 12
	s_cselect_b32 s29, s2, s27
	s_cselect_b32 s28, s3, s26
	s_cselect_b32 s27, s15, s56
	s_cselect_b32 s26, s17, s55
	s_add_i32 m0, s40, 0xc000
	ds_read_b128 v[188:191], v165
	ds_read_b128 v[192:195], v165 offset:1024
	ds_read_b128 v[196:199], v165 offset:2048
	ds_read_b128 v[200:203], v165 offset:3072
	ds_read_b128 v[204:207], v165 offset:4096
	ds_read_b128 v[208:211], v165 offset:5120
	ds_read_b128 v[212:215], v165 offset:6144
	ds_read_b128 v[216:219], v165 offset:7168
	global_load_lds_dwordx4 v142, s[24:25]
	s_add_i32 m0, s40, 0xe000
	s_nop 0
	global_load_lds_dwordx4 v144, s[24:25]
	s_waitcnt vmcnt(8)
	s_waitcnt lgkmcnt(0)
	s_barrier
	s_waitcnt lgkmcnt(0)
	v_mfma_f32_16x16x32_bf16 v[128:131], v[132:135], v[188:191], v[128:131]
	v_mfma_f32_16x16x32_bf16 v[120:123], v[150:153], v[188:191], v[120:123]
	v_mfma_f32_16x16x32_bf16 v[112:115], v[132:135], v[196:199], v[112:115]
	v_mfma_f32_16x16x32_bf16 v[104:107], v[150:153], v[196:199], v[104:107]
	v_mfma_f32_16x16x32_bf16 v[96:99], v[132:135], v[204:207], v[96:99]
	v_mfma_f32_16x16x32_bf16 v[88:91], v[150:153], v[204:207], v[88:91]
	v_mfma_f32_16x16x32_bf16 v[80:83], v[132:135], v[212:215], v[80:83]
	v_mfma_f32_16x16x32_bf16 v[72:75], v[150:153], v[212:215], v[72:75]
	v_mfma_f32_16x16x32_bf16 v[128:131], v[146:149], v[192:195], v[128:131]
	v_mfma_f32_16x16x32_bf16 v[120:123], v[154:157], v[192:195], v[120:123]
	v_mfma_f32_16x16x32_bf16 v[112:115], v[146:149], v[200:203], v[112:115]
	v_mfma_f32_16x16x32_bf16 v[104:107], v[154:157], v[200:203], v[104:107]
	v_mfma_f32_16x16x32_bf16 v[96:99], v[146:149], v[208:211], v[96:99]
	v_mfma_f32_16x16x32_bf16 v[88:91], v[154:157], v[208:211], v[88:91]
	v_mfma_f32_16x16x32_bf16 v[80:83], v[146:149], v[216:219], v[80:83]
	v_mfma_f32_16x16x32_bf16 v[72:75], v[154:157], v[216:219], v[72:75]
	v_mfma_f32_16x16x32_bf16 v[124:127], v[158:161], v[188:191], v[124:127]
	v_mfma_f32_16x16x32_bf16 v[116:119], v[170:173], v[188:191], v[116:119]
	v_mfma_f32_16x16x32_bf16 v[108:111], v[158:161], v[196:199], v[108:111]
	v_mfma_f32_16x16x32_bf16 v[100:103], v[170:173], v[196:199], v[100:103]
	v_mfma_f32_16x16x32_bf16 v[92:95], v[158:161], v[204:207], v[92:95]
	v_mfma_f32_16x16x32_bf16 v[84:87], v[170:173], v[204:207], v[84:87]
	v_mfma_f32_16x16x32_bf16 v[76:79], v[158:161], v[212:215], v[76:79]
	v_mfma_f32_16x16x32_bf16 v[68:71], v[170:173], v[212:215], v[68:71]
	v_mfma_f32_16x16x32_bf16 v[124:127], v[166:169], v[192:195], v[124:127]
	v_mfma_f32_16x16x32_bf16 v[116:119], v[174:177], v[192:195], v[116:119]
	v_mfma_f32_16x16x32_bf16 v[108:111], v[166:169], v[200:203], v[108:111]
	v_mfma_f32_16x16x32_bf16 v[100:103], v[174:177], v[200:203], v[100:103]
	v_mfma_f32_16x16x32_bf16 v[92:95], v[166:169], v[208:211], v[92:95]
	v_mfma_f32_16x16x32_bf16 v[84:87], v[174:177], v[208:211], v[84:87]
	v_mfma_f32_16x16x32_bf16 v[76:79], v[166:169], v[216:219], v[76:79]
	v_mfma_f32_16x16x32_bf16 v[68:71], v[174:177], v[216:219], v[68:71]
	s_barrier
; #define PG8_STAGE(bufoff, gbase, voff) do { _Pragma("unroll") for (int _i = 0; _i < 2; ++_i) \
;         __builtin_amdgcn_global_load_lds((const unsigned*)((const char*)(gbase) + (voff)[_i]), (PG8_LAS unsigned*)(lds + (bufoff) + ldsw + _i * 8192), 16, 0, 0); } while (0)
; #define PG8_LDA(dst, b, h) do { _Pragma("unroll") for (int m = 0; m < 4; ++m) _Pragma("unroll") for (int k = 0; k < 2; ++k) dst[m][k] = *(const PG8_LAS bf16x8*)(lds + PG8_SA(b, h) + aoff + m * 2048 + k * 1024); } while (0)
; #define PG8_LDB(dst, b, h) do { _Pragma("unroll") for (int n = 0; n < 2; ++n) _Pragma("unroll") for (int k = 0; k < 2; ++k) dst[n][k] = *(const PG8_LAS bf16x8*)(lds + PG8_SB(b, h) + boff + n * 2048 + k * 1024); } while (0)
; #define PG8_MMA(ai, bj, At, Bt) do { __builtin_amdgcn_s_setprio(1); _Pragma("unroll") for (int m = 0; m < 4; ++m) _Pragma("unroll") for (int n = 0; n < 2; ++n) _Pragma("unroll") for (int k = 0; k < 2; ++k) \
;         acc[ai][bj][m][n] = __builtin_amdgcn_mfma_f32_16x16x32_bf16(Bt[n][k], At[m][k], acc[ai][bj][m][n], 0, 0, 0); __builtin_amdgcn_s_setprio(0); } while (0)
; #define PG8_WAIT_V(n) asm volatile("s_waitcnt vmcnt(" #n ")" ::: "memory")
; #define PG8_WAIT_L(n) asm volatile("s_waitcnt lgkmcnt(" #n ")" ::: "memory")
; #define PG8_BAR __builtin_amdgcn_s_barrier()
; #define PG8_SCHED __builtin_amdgcn_sched_barrier(0)
; template <class Epi, class Sched, bool ALIGN_EPI = false, bool SP2 = false>
; __device__ __forceinline__ void gemm_phase(PG8_LAS unsigned char* lds, const Gemm g, const Sched& S, const Epi& E, const int tid_) {
;     ...
;             PG8_LDA(At, 0, 1); PG8_STAGE(PG8_SB(0, 0), b2, voffB); PG8_STAGE(PG8_SB(0, 1), b2 + hstepB, voffB); PG8_STAGE(PG8_SA(0, 0), a2, voffA);
;             PG8_WAIT_V(8); PG8_WAIT_L(0); PG8_BAR; PG8_MMA(1, 0, At, B0); PG8_MMA(1, 1, At, B1); PG8_BAR; PG8_SCHED;
;             PG8_LDB(B0, 1, 0); PG8_LDB(B1, 1, 1); PG8_SCHED; PG8_LDA(At, 1, 0); PG8_STAGE(PG8_SA(0, 1), a2 + hstep, voffA);
;             PG8_WAIT_V(8); PG8_WAIT_L(0); PG8_BAR; PG8_MMA(0, 0, At, B0); PG8_MMA(0, 1, At, B1); PG8_BAR; PG8_SCHED;
	s_mov_b32 m0, s35
	s_add_u32 s58, s26, 0x40000
	ds_read_b128 v[188:191], v165 offset:16384
	ds_read_b128 v[192:195], v165 offset:17408
	ds_read_b128 v[196:199], v165 offset:18432
	ds_read_b128 v[200:203], v165 offset:19456
	ds_read_b128 v[204:207], v165 offset:20480
	ds_read_b128 v[208:211], v165 offset:21504
	ds_read_b128 v[212:215], v165 offset:22528
	ds_read_b128 v[216:219], v165 offset:23552
	global_load_lds_dwordx4 v2, s[26:27]
	s_mov_b32 m0, s36
	s_addc_u32 s59, s27, 0
	global_load_lds_dwordx4 v0, s[26:27]
	s_mov_b32 m0, s38
	s_nop 0
	global_load_lds_dwordx4 v2, s[58:59]
	s_mov_b32 m0, s39
	s_nop 0
	global_load_lds_dwordx4 v0, s[58:59]
	s_mov_b32 m0, s40
	s_nop 0
	global_load_lds_dwordx4 v138, s[28:29]
	s_mov_b32 m0, s41
	s_nop 0
	global_load_lds_dwordx4 v136, s[28:29]
	s_waitcnt vmcnt(8)
	s_waitcnt lgkmcnt(0)
	s_barrier
	s_waitcnt lgkmcnt(0)
	v_mfma_f32_16x16x32_bf16 v[64:67], v[132:135], v[188:191], v[64:67]
	v_mfma_f32_16x16x32_bf16 v[56:59], v[150:153], v[188:191], v[56:59]
	v_mfma_f32_16x16x32_bf16 v[48:51], v[132:135], v[196:199], v[48:51]
	v_mfma_f32_16x16x32_bf16 v[40:43], v[150:153], v[196:199], v[40:43]
	v_mfma_f32_16x16x32_bf16 v[32:35], v[132:135], v[204:207], v[32:35]
	v_mfma_f32_16x16x32_bf16 v[24:27], v[150:153], v[204:207], v[24:27]
	v_mfma_f32_16x16x32_bf16 v[16:19], v[132:135], v[212:215], v[16:19]
	v_mfma_f32_16x16x32_bf16 v[8:11], v[150:153], v[212:215], v[8:11]
	v_mfma_f32_16x16x32_bf16 v[64:67], v[146:149], v[192:195], v[64:67]
	v_mfma_f32_16x16x32_bf16 v[56:59], v[154:157], v[192:195], v[56:59]
	v_mfma_f32_16x16x32_bf16 v[48:51], v[146:149], v[200:203], v[48:51]
	v_mfma_f32_16x16x32_bf16 v[40:43], v[154:157], v[200:203], v[40:43]
	v_mfma_f32_16x16x32_bf16 v[32:35], v[146:149], v[208:211], v[32:35]
	v_mfma_f32_16x16x32_bf16 v[24:27], v[154:157], v[208:211], v[24:27]
	v_mfma_f32_16x16x32_bf16 v[16:19], v[146:149], v[216:219], v[16:19]
	v_mfma_f32_16x16x32_bf16 v[8:11], v[154:157], v[216:219], v[8:11]
	v_mfma_f32_16x16x32_bf16 v[60:63], v[158:161], v[188:191], v[60:63]
	v_mfma_f32_16x16x32_bf16 v[52:55], v[170:173], v[188:191], v[52:55]
	v_mfma_f32_16x16x32_bf16 v[44:47], v[158:161], v[196:199], v[44:47]
	v_mfma_f32_16x16x32_bf16 v[36:39], v[170:173], v[196:199], v[36:39]
	v_mfma_f32_16x16x32_bf16 v[28:31], v[158:161], v[204:207], v[28:31]
	v_mfma_f32_16x16x32_bf16 v[20:23], v[170:173], v[204:207], v[20:23]
	v_mfma_f32_16x16x32_bf16 v[12:15], v[158:161], v[212:215], v[12:15]
	v_mfma_f32_16x16x32_bf16 v[4:7], v[170:173], v[212:215], v[4:7]
	v_mfma_f32_16x16x32_bf16 v[60:63], v[166:169], v[192:195], v[60:63]
	v_mfma_f32_16x16x32_bf16 v[52:55], v[174:177], v[192:195], v[52:55]
	v_mfma_f32_16x16x32_bf16 v[44:47], v[166:169], v[200:203], v[44:47]
	v_mfma_f32_16x16x32_bf16 v[36:39], v[174:177], v[200:203], v[36:39]
	v_mfma_f32_16x16x32_bf16 v[28:31], v[166:169], v[208:211], v[28:31]
	v_mfma_f32_16x16x32_bf16 v[20:23], v[174:177], v[208:211], v[20:23]
	v_mfma_f32_16x16x32_bf16 v[12:15], v[166:169], v[216:219], v[12:15]
	v_mfma_f32_16x16x32_bf16 v[4:7], v[174:177], v[216:219], v[4:7]
	s_barrier
	v_add_u32_e32 v154, s44, v163
	v_add_u32_e32 v174, s49, v163
	ds_read_b128 v[132:135], v154
	ds_read_b128 v[146:149], v154 offset:1024
	ds_read_b128 v[150:153], v154 offset:2048
	ds_read_b128 v[154:157], v154 offset:3072
	ds_read_b128 v[158:161], v174
	ds_read_b128 v[166:169], v174 offset:1024
	ds_read_b128 v[170:173], v174 offset:2048
	ds_read_b128 v[174:177], v174 offset:3072
	s_add_u32 s28, s28, 0x40000
	s_addc_u32 s29, s29, 0
	s_mov_b32 m0, s42
	ds_read_b128 v[188:191], v165 offset:32768
	ds_read_b128 v[192:195], v165 offset:33792
	ds_read_b128 v[196:199], v165 offset:34816
	ds_read_b128 v[200:203], v165 offset:35840
	ds_read_b128 v[204:207], v165 offset:36864
	ds_read_b128 v[208:211], v165 offset:37888
	ds_read_b128 v[212:215], v165 offset:38912
	ds_read_b128 v[216:219], v165 offset:39936
	global_load_lds_dwordx4 v138, s[28:29]
	s_mov_b32 m0, s43
	s_nop 0
	global_load_lds_dwordx4 v136, s[28:29]
	s_waitcnt vmcnt(8)
	s_waitcnt lgkmcnt(0)
	s_barrier
; #define PG8_STAGE(bufoff, gbase, voff) do { _Pragma("unroll") for (int _i = 0; _i < 2; ++_i) \
;         __builtin_amdgcn_global_load_lds((const unsigned*)((const char*)(gbase) + (voff)[_i]), (PG8_LAS unsigned*)(lds + (bufoff) + ldsw + _i * 8192), 16, 0, 0); } while (0)
; #define PG8_LDA(dst, b, h) do { _Pragma("unroll") for (int m = 0; m < 4; ++m) _Pragma("unroll") for (int k = 0; k < 2; ++k) dst[m][k] = *(const PG8_LAS bf16x8*)(lds + PG8_SA(b, h) + aoff + m * 2048 + k * 1024); } while (0)
; #define PG8_MMA(ai, bj, At, Bt) do { __builtin_amdgcn_s_setprio(1); _Pragma("unroll") for (int m = 0; m < 4; ++m) _Pragma("unroll") for (int n = 0; n < 2; ++n) _Pragma("unroll") for (int k = 0; k < 2; ++k) \
;         acc[ai][bj][m][n] = __builtin_amdgcn_mfma_f32_16x16x32_bf16(Bt[n][k], At[m][k], acc[ai][bj][m][n], 0, 0, 0); __builtin_amdgcn_s_setprio(0); } while (0)
; #define PG8_WAIT_V(n) asm volatile("s_waitcnt vmcnt(" #n ")" ::: "memory")
; #define PG8_WAIT_L(n) asm volatile("s_waitcnt lgkmcnt(" #n ")" ::: "memory")
; #define PG8_BAR __builtin_amdgcn_s_barrier()
; #define PG8_SCHED __builtin_amdgcn_sched_barrier(0)
; template <class Epi, class Sched, bool ALIGN_EPI = false, bool SP2 = false>
; __device__ __forceinline__ void gemm_phase(PG8_LAS unsigned char* lds, const Gemm g, const Sched& S, const Epi& E, const int tid_) {
;     ...
;             PG8_WAIT_V(8); PG8_WAIT_L(0); PG8_BAR; PG8_MMA(0, 0, At, B0); PG8_MMA(0, 1, At, B1); PG8_BAR; PG8_SCHED;
;             PG8_LDA(At, 1, 1); PG8_STAGE(PG8_SB(1, 0), b3, voffB); PG8_STAGE(PG8_SB(1, 1), b3 + hstepB, voffB); PG8_STAGE(PG8_SA(1, 0), a3, voffA);
;             PG8_WAIT_V(8); PG8_WAIT_L(0); PG8_BAR; PG8_MMA(1, 0, At, B0); PG8_MMA(1, 1, At, B1); PG8_BAR; PG8_SCHED;
	s_waitcnt lgkmcnt(0)
	v_mfma_f32_16x16x32_bf16 v[128:131], v[132:135], v[188:191], v[128:131]
	v_mfma_f32_16x16x32_bf16 v[120:123], v[150:153], v[188:191], v[120:123]
	v_mfma_f32_16x16x32_bf16 v[112:115], v[132:135], v[196:199], v[112:115]
	v_mfma_f32_16x16x32_bf16 v[104:107], v[150:153], v[196:199], v[104:107]
	v_mfma_f32_16x16x32_bf16 v[96:99], v[132:135], v[204:207], v[96:99]
	v_mfma_f32_16x16x32_bf16 v[88:91], v[150:153], v[204:207], v[88:91]
	v_mfma_f32_16x16x32_bf16 v[80:83], v[132:135], v[212:215], v[80:83]
	v_mfma_f32_16x16x32_bf16 v[72:75], v[150:153], v[212:215], v[72:75]
	v_mfma_f32_16x16x32_bf16 v[128:131], v[146:149], v[192:195], v[128:131]
	v_mfma_f32_16x16x32_bf16 v[120:123], v[154:157], v[192:195], v[120:123]
	v_mfma_f32_16x16x32_bf16 v[112:115], v[146:149], v[200:203], v[112:115]
	v_mfma_f32_16x16x32_bf16 v[104:107], v[154:157], v[200:203], v[104:107]
	v_mfma_f32_16x16x32_bf16 v[96:99], v[146:149], v[208:211], v[96:99]
	v_mfma_f32_16x16x32_bf16 v[88:91], v[154:157], v[208:211], v[88:91]
	v_mfma_f32_16x16x32_bf16 v[80:83], v[146:149], v[216:219], v[80:83]
	v_mfma_f32_16x16x32_bf16 v[72:75], v[154:157], v[216:219], v[72:75]
	v_mfma_f32_16x16x32_bf16 v[124:127], v[158:161], v[188:191], v[124:127]
	v_mfma_f32_16x16x32_bf16 v[116:119], v[170:173], v[188:191], v[116:119]
	v_mfma_f32_16x16x32_bf16 v[108:111], v[158:161], v[196:199], v[108:111]
	v_mfma_f32_16x16x32_bf16 v[100:103], v[170:173], v[196:199], v[100:103]
	v_mfma_f32_16x16x32_bf16 v[92:95], v[158:161], v[204:207], v[92:95]
	v_mfma_f32_16x16x32_bf16 v[84:87], v[170:173], v[204:207], v[84:87]
	v_mfma_f32_16x16x32_bf16 v[76:79], v[158:161], v[212:215], v[76:79]
	v_mfma_f32_16x16x32_bf16 v[68:71], v[170:173], v[212:215], v[68:71]
	v_mfma_f32_16x16x32_bf16 v[124:127], v[166:169], v[192:195], v[124:127]
	v_mfma_f32_16x16x32_bf16 v[116:119], v[174:177], v[192:195], v[116:119]
	v_mfma_f32_16x16x32_bf16 v[108:111], v[166:169], v[200:203], v[108:111]
	v_mfma_f32_16x16x32_bf16 v[100:103], v[174:177], v[200:203], v[100:103]
	v_mfma_f32_16x16x32_bf16 v[92:95], v[166:169], v[208:211], v[92:95]
	v_mfma_f32_16x16x32_bf16 v[84:87], v[174:177], v[208:211], v[84:87]
	v_mfma_f32_16x16x32_bf16 v[76:79], v[166:169], v[216:219], v[76:79]
	v_mfma_f32_16x16x32_bf16 v[68:71], v[174:177], v[216:219], v[68:71]
	s_barrier
	s_mov_b32 m0, s45
	s_add_u32 s58, s26, 0x80
	s_addc_u32 s59, s27, 0
	s_add_u32 s26, s26, 0x40080
	s_addc_u32 s27, s27, 0
	ds_read_b128 v[188:191], v165 offset:49152
	ds_read_b128 v[192:195], v165 offset:50176
	ds_read_b128 v[196:199], v165 offset:51200
	ds_read_b128 v[200:203], v165 offset:52224
	ds_read_b128 v[204:207], v165 offset:53248
	ds_read_b128 v[208:211], v165 offset:54272
	ds_read_b128 v[212:215], v165 offset:55296
	ds_read_b128 v[216:219], v165 offset:56320
	global_load_lds_dwordx4 v2, s[58:59]
	s_mov_b32 m0, s46
	s_add_u32 s28, s28, 0xfffc0080
	s_addc_u32 s29, s29, -1
	global_load_lds_dwordx4 v0, s[58:59]
	s_mov_b32 m0, s50
	s_nop 0
	global_load_lds_dwordx4 v2, s[26:27]
	s_mov_b32 m0, s51
	s_nop 0
	global_load_lds_dwordx4 v0, s[26:27]
	s_mov_b32 m0, s47
	s_nop 0
	global_load_lds_dwordx4 v138, s[28:29]
	s_mov_b32 m0, s48
	s_nop 0
	global_load_lds_dwordx4 v136, s[28:29]
	s_waitcnt vmcnt(8)
	s_waitcnt lgkmcnt(0)
	s_barrier
	s_waitcnt lgkmcnt(0)
	v_mfma_f32_16x16x32_bf16 v[64:67], v[132:135], v[188:191], v[64:67]
	v_mfma_f32_16x16x32_bf16 v[56:59], v[150:153], v[188:191], v[56:59]
	v_mfma_f32_16x16x32_bf16 v[48:51], v[132:135], v[196:199], v[48:51]
	v_mfma_f32_16x16x32_bf16 v[40:43], v[150:153], v[196:199], v[40:43]
	v_mfma_f32_16x16x32_bf16 v[32:35], v[132:135], v[204:207], v[32:35]
	v_mfma_f32_16x16x32_bf16 v[24:27], v[150:153], v[204:207], v[24:27]
	v_mfma_f32_16x16x32_bf16 v[16:19], v[132:135], v[212:215], v[16:19]
	v_mfma_f32_16x16x32_bf16 v[8:11], v[150:153], v[212:215], v[8:11]
	v_mfma_f32_16x16x32_bf16 v[64:67], v[146:149], v[192:195], v[64:67]
	v_mfma_f32_16x16x32_bf16 v[56:59], v[154:157], v[192:195], v[56:59]
	v_mfma_f32_16x16x32_bf16 v[48:51], v[146:149], v[200:203], v[48:51]
	v_mfma_f32_16x16x32_bf16 v[40:43], v[154:157], v[200:203], v[40:43]
	v_mfma_f32_16x16x32_bf16 v[32:35], v[146:149], v[208:211], v[32:35]
	v_mfma_f32_16x16x32_bf16 v[24:27], v[154:157], v[208:211], v[24:27]
	v_mfma_f32_16x16x32_bf16 v[16:19], v[146:149], v[216:219], v[16:19]
	v_mfma_f32_16x16x32_bf16 v[8:11], v[154:157], v[216:219], v[8:11]
	v_mfma_f32_16x16x32_bf16 v[60:63], v[158:161], v[188:191], v[60:63]
	v_mfma_f32_16x16x32_bf16 v[52:55], v[170:173], v[188:191], v[52:55]
	v_mfma_f32_16x16x32_bf16 v[44:47], v[158:161], v[196:199], v[44:47]
	v_mfma_f32_16x16x32_bf16 v[36:39], v[170:173], v[196:199], v[36:39]
	v_mfma_f32_16x16x32_bf16 v[28:31], v[158:161], v[204:207], v[28:31]
	v_mfma_f32_16x16x32_bf16 v[20:23], v[170:173], v[204:207], v[20:23]
	v_mfma_f32_16x16x32_bf16 v[12:15], v[158:161], v[212:215], v[12:15]
	v_mfma_f32_16x16x32_bf16 v[4:7], v[170:173], v[212:215], v[4:7]
	v_mfma_f32_16x16x32_bf16 v[60:63], v[166:169], v[192:195], v[60:63]
	v_mfma_f32_16x16x32_bf16 v[52:55], v[174:177], v[192:195], v[52:55]
	v_mfma_f32_16x16x32_bf16 v[44:47], v[166:169], v[200:203], v[44:47]
	v_mfma_f32_16x16x32_bf16 v[36:39], v[174:177], v[200:203], v[36:39]
	v_mfma_f32_16x16x32_bf16 v[28:31], v[166:169], v[208:211], v[28:31]
	v_mfma_f32_16x16x32_bf16 v[20:23], v[174:177], v[208:211], v[20:23]
	v_mfma_f32_16x16x32_bf16 v[12:15], v[166:169], v[216:219], v[12:15]
	v_mfma_f32_16x16x32_bf16 v[4:7], v[174:177], v[216:219], v[4:7]
	s_barrier
	s_add_i32 s57, s57, 2
	s_add_u32 s24, s24, 0x100
	s_addc_u32 s25, s25, 0
	s_add_u32 s55, s55, 0x100
	s_addc_u32 s56, s56, 0
	s_cmp_gt_u32 s57, 13
	s_cbranch_scc0 .LBB0_24
	s_and_b64 vcc, exec, s[12:13]
	s_cbranch_vccz .LBB0_27
	s_barrier
